# GEMM tile prologue: per-tile vmcnt(3)/(2) waits (which drained the previous tile's epilogue stores) replaced by one drain at phase entry
# speedup vs baseline: 1.0125x; 1.0078x over previous
.LBB0_448:
	v_readlane_b32 s2, v251, 0
	s_cmp_ge_i32 s2, s78
	s_cbranch_scc1 .LBB0_511
	s_lshl_b64 s[2:3], s[0:1], 17
	s_lshl_b64 s[20:21], s[0:1], 21
	s_mul_hi_i32 s28, s0, 0x580000
	s_mul_i32 s34, s0, 0x580000
	s_lshl_b32 s0, s96, 1
	v_readlane_b32 s4, v253, 33
	s_or_b32 s0, s0, s92
	v_readlane_b32 s8, v253, 37
	s_mul_hi_i32 s40, s0, 0x580000
	s_mul_i32 s41, s0, 0x580000
	s_mul_hi_i32 s42, s0, 0xb00000
	s_mul_i32 s43, s0, 0xb00000
	v_readlane_b32 s5, v253, 34
	v_readlane_b32 s6, v253, 35
	v_readlane_b32 s7, v253, 36
	v_readlane_b32 s9, v253, 38
	v_readlane_b32 s10, v253, 39
	v_readlane_b32 s11, v253, 40
	s_mov_b64 s[0:1], s[36:37]
	s_add_u32 s36, s8, s2
	s_addc_u32 s37, s9, s3
	v_readlane_b32 s4, v254, 1
	s_lshl_b64 s[0:1], s[0:1], 2
	v_readlane_b32 s6, v254, 3
	v_readlane_b32 s7, v254, 4
	s_add_u32 s0, s6, s0
	s_addc_u32 s1, s7, s1
	v_readlane_b32 s44, v251, 38
	v_writelane_b32 v255, s0, 6
	v_readlane_b32 s58, v251, 52
	v_readlane_b32 s59, v251, 53
	v_writelane_b32 v255, s1, 7
	s_add_u32 s0, s58, s20
	v_readlane_b32 s56, v251, 50
	s_addc_u32 s1, s59, s21
	v_readlane_b32 s57, v251, 51
	s_add_u32 s60, s56, s20
	v_readlane_b32 s54, v251, 48
	s_addc_u32 s61, s57, s21
	v_readlane_b32 s55, v251, 49
	s_add_u32 s62, s54, s20
	v_and_b32_e32 v133, 31, v203
	s_waitcnt vmcnt(5)
	v_mul_i32_i24_e32 v5, 0x60, v201
	v_readlane_b32 s52, v251, 46
	s_addc_u32 s63, s55, s21
	s_waitcnt vmcnt(4)
	v_or_b32_e32 v6, v5, v133
	v_readlane_b32 s53, v251, 47
	s_add_u32 s64, s52, s20
	v_lshlrev_b32_e32 v4, 4, v203
	v_lshlrev_b32_e32 v138, 7, v6
	v_lshlrev_b32_e32 v6, 7, v203
	v_readlane_b32 s50, v251, 44
	s_addc_u32 s65, s53, s21
	v_lshrrev_b32_e32 v2, 5, v203
	v_and_b32_e32 v4, 0xfffffc00, v4
	v_and_b32_e32 v140, 0x6f80, v6
	v_bfe_u32 v6, v203, 1, 3
	v_readlane_b32 s51, v251, 45
	s_add_u32 s66, s50, s34
	v_add_u32_e32 v137, 32, v4
	v_bfe_u32 v4, v203, 5, 1
	v_bitop3_b32 v2, v2, v6, 1 bitop3:0x6c
	v_readlane_b32 s48, v251, 42
	s_addc_u32 s67, s51, s28
	v_lshrrev_b32_e32 v3, 4, v203
	v_lshlrev_b32_e32 v141, 4, v2
	v_bitop3_b32 v2, v4, v6, 2 bitop3:0x36
	v_readlane_b32 s49, v251, 43
	s_add_u32 s68, s48, s41
	v_xor_b32_e32 v0, v3, v203
	v_lshlrev_b32_e32 v142, 4, v2
	v_bitop3_b32 v2, v4, v6, 4 bitop3:0x36
	v_readlane_b32 s46, v251, 40
	s_addc_u32 s69, s49, s40
	v_lshlrev_b32_e32 v0, 3, v0
	v_lshlrev_b32_e32 v143, 4, v2
	v_bitop3_b32 v2, v4, v6, 6 bitop3:0x36
	v_readlane_b32 s47, v251, 41
	s_add_u32 s46, s46, s43
	v_and_b32_e32 v0, 56, v0
	v_lshlrev_b32_e32 v144, 4, v2
	v_and_b32_e32 v146, 1, v203
	v_bitop3_b32 v2, v3, 7, v203 bitop3:0x48
	v_readlane_b32 s92, v251, 0
	s_mov_b64 s[50:51], s[0:1]
	s_addc_u32 s47, s47, s42
	v_ashrrev_i32_e32 v136, 3, v203
	v_and_b32_e32 v139, 0xc0, v203
	v_lshl_or_b32 v145, v4, 2, v5
	v_cmp_eq_u32_e64 s[40:41], 0, v146
	v_and_b32_e32 v147, 30, v203
	v_lshlrev_b32_e32 v98, 4, v2
	v_mov_b32_e32 v99, v1
	v_lshlrev_b32_e32 v0, 1, v0
	s_mov_b32 s79, s92
	v_readlane_b32 s12, v253, 41
	v_readlane_b32 s13, v253, 42
	v_readlane_b32 s14, v253, 43
	v_readlane_b32 s15, v253, 44
	v_readlane_b32 s16, v253, 45
	v_readlane_b32 s17, v253, 46
	v_readlane_b32 s18, v253, 47
	v_readlane_b32 s19, v253, 48
	v_readlane_b32 s5, v254, 2
	v_readlane_b32 s8, v254, 5
	v_readlane_b32 s9, v254, 6
	v_readlane_b32 s10, v254, 7
	v_readlane_b32 s11, v254, 8
	v_readlane_b32 s45, v251, 39
	s_waitcnt vmcnt(0)
	s_branch .LBB0_451

.LBB0_485:
	s_lshl_b32 s8, s20, 6
	s_mov_b32 s9, 0
	s_lshl_b32 s10, s28, 6
	s_mov_b32 s11, 0
	s_and_b32 s76, s92, 63
	s_mulk_i32 s76, 0xc0
	v_add_u32_e32 v8, s76, v136
	v_ashrrev_i32_e32 v9, 31, v8
	s_lshl_b32 s77, s84, 8
	v_mul_lo_u32 v10, s20, v9
	v_mul_lo_u32 v11, s21, v8
	v_mad_u64_u32 v[8:9], s[86:87], s20, v8, 0
	v_add3_u32 v9, v9, v10, v11
	v_add_u32_e32 v10, s77, v136
	v_mad_u64_u32 v[12:13], s[86:87], v10, s28, 0
	v_ashrrev_i32_e32 v11, 31, v10
	v_mov_b32_e32 v14, v13
	v_mad_u64_u32 v[14:15], s[86:87], v11, s28, v[14:15]
	v_lshl_add_u64 v[8:9], v[8:9], 1, s[56:57]
	v_mov_b32_e32 v13, v14
	v_readfirstlane_b32 s84, v137
	v_add_u32_e32 v14, 0x2000, v137
	v_lshl_add_u64 v[8:9], v[8:9], 0, v[0:1]
	s_mov_b32 m0, s84
	s_lshl_b64 s[86:87], s[20:21], 7
	v_readfirstlane_b32 s84, v14
	v_add_u32_e32 v14, 0x4000, v137
	global_load_lds_dwordx4 v[8:9], off
	v_lshl_add_u64 v[8:9], v[8:9], 0, s[86:87]
	s_mov_b32 m0, s84
	v_readfirstlane_b32 s84, v14
	v_lshl_add_u64 v[12:13], v[12:13], 1, s[2:3]
	global_load_lds_dwordx4 v[8:9], off
	v_lshl_add_u64 v[8:9], v[8:9], 0, s[86:87]
	s_mov_b32 m0, s84
	s_lshl_b64 s[86:87], s[28:29], 7
	global_load_lds_dwordx4 v[8:9], off
	v_lshl_add_u64 v[8:9], v[12:13], 0, v[0:1]
	v_add_u32_e32 v12, 0x6000, v137
	s_and_b32 s34, s79, 63
	v_readfirstlane_b32 s84, v12
	v_add_u32_e32 v12, 0x8000, v137
	s_mov_b32 m0, s84
	v_readfirstlane_b32 s84, v12
	v_add_u32_e32 v12, 0xa000, v137
	global_load_lds_dwordx4 v[8:9], off
	v_lshl_add_u64 v[8:9], v[8:9], 0, s[86:87]
	s_mov_b32 m0, s84
	v_readfirstlane_b32 s84, v12
	v_add_u32_e32 v12, 0xc000, v137
	global_load_lds_dwordx4 v[8:9], off
	v_lshl_add_u64 v[8:9], v[8:9], 0, s[86:87]
	s_mov_b32 m0, s84
	v_readfirstlane_b32 s84, v12
	global_load_lds_dwordx4 v[8:9], off
	v_lshl_add_u64 v[8:9], v[8:9], 0, s[86:87]
	s_mov_b32 m0, s84
	s_mulk_i32 s34, 0xc0
	global_load_lds_dwordx4 v[8:9], off
	s_mov_b64 s[4:5], 0x80
	v_lshl_add_u64 v[8:9], s[56:57], 0, v[98:99]
	v_add_u32_e32 v2, s34, v136
	v_lshl_add_u64 v[8:9], v[8:9], 0, s[4:5]
	s_lshl_b32 s86, s20, 1
	v_ashrrev_i32_e32 v3, 31, v2
	v_mad_u64_u32 v[100:101], s[56:57], s86, v2, v[8:9]
	v_lshlrev_b64 v[4:5], 1, v[2:3]
	s_mov_b64 s[6:7], 0x100
	s_lshr_b64 s[56:57], s[20:21], 31
	v_lshl_add_u64 v[6:7], v[4:5], 0, s[6:7]
	v_mul_lo_u32 v2, s56, v2
	v_mul_lo_u32 v3, s86, v3
	v_lshl_add_u64 v[4:5], v[4:5], 0, s[4:5]
	v_add3_u32 v101, v2, v101, v3
	v_mul_lo_u32 v2, s20, v7
	v_mul_lo_u32 v3, s21, v6
	v_mad_u64_u32 v[102:103], s[56:57], s20, v6, v[8:9]
	v_add3_u32 v103, v3, v103, v2
	v_mul_lo_u32 v2, s20, v5
	v_mul_lo_u32 v3, s21, v4
	v_mad_u64_u32 v[104:105], s[20:21], s20, v4, v[8:9]
	v_add3_u32 v105, v3, v105, v2
	v_lshl_add_u64 v[2:3], s[2:3], 0, v[98:99]
	v_lshl_add_u64 v[2:3], v[2:3], 0, s[4:5]
	v_lshlrev_b64 v[4:5], 1, v[10:11]
	v_mad_u64_u32 v[106:107], s[2:3], v4, s28, v[2:3]
	v_alignbit_b32 v7, v11, v10, 31
	v_mov_b32_e32 v6, v107
	v_mad_u64_u32 v[6:7], s[2:3], v7, s28, v[6:7]
	v_mov_b32_e32 v107, v6
	v_lshl_add_u64 v[6:7], v[4:5], 0, s[6:7]
	v_mad_u64_u32 v[108:109], s[2:3], v6, s28, v[2:3]
	v_mov_b32_e32 v6, v109
	v_mad_u64_u32 v[6:7], s[2:3], v7, s28, v[6:7]
	s_mov_b64 s[2:3], 0x180
	v_mov_b32_e32 v109, v6
	v_lshl_add_u64 v[6:7], v[4:5], 0, s[2:3]
	v_lshl_add_u64 v[4:5], v[4:5], 0, s[4:5]
	v_mad_u64_u32 v[110:111], s[2:3], v6, s28, v[2:3]
	v_mad_u64_u32 v[112:113], s[2:3], v4, s28, v[2:3]
	v_mov_b32_e32 v6, v111
	v_mov_b32_e32 v2, v113
	v_mad_u64_u32 v[6:7], s[2:3], v7, s28, v[6:7]
	v_mad_u64_u32 v[2:3], s[2:3], v5, s28, v[2:3]
	v_mov_b32_e32 v113, v2
	s_lshl_b64 s[2:3], s[28:29], 1
	v_mov_b32_e32 v2, 0
	s_mov_b32 s34, 1
	s_lshr_b32 s84, s28, 6
	v_mov_b32_e32 v111, v6
	s_and_b32 s20, s2, 0xffffff80
	s_mov_b64 s[2:3], 0
	v_mov_b32_e32 v3, v2
	v_mov_b32_e32 v4, v2
	v_mov_b32_e32 v5, v2
	v_mov_b32_e32 v6, v2
	v_mov_b32_e32 v7, v2
	v_mov_b32_e32 v8, v2
	v_mov_b32_e32 v9, v2
	v_mov_b32_e32 v10, v2
	v_mov_b32_e32 v11, v2
	v_mov_b32_e32 v12, v2
	v_mov_b32_e32 v13, v2
	v_mov_b32_e32 v14, v2
	v_mov_b32_e32 v15, v2
	v_mov_b32_e32 v16, v2
	v_mov_b32_e32 v17, v2
	v_mov_b32_e32 v18, v2
	v_mov_b32_e32 v19, v2
	v_mov_b32_e32 v20, v2
	v_mov_b32_e32 v21, v2
	v_mov_b32_e32 v22, v2
	v_mov_b32_e32 v23, v2
	v_mov_b32_e32 v24, v2
	v_mov_b32_e32 v25, v2
	v_mov_b32_e32 v26, v2
	v_mov_b32_e32 v27, v2
	v_mov_b32_e32 v28, v2
	v_mov_b32_e32 v29, v2
	v_mov_b32_e32 v30, v2
	v_mov_b32_e32 v31, v2
	v_mov_b32_e32 v32, v2
	v_mov_b32_e32 v33, v2
	v_mov_b32_e32 v34, v2
	v_mov_b32_e32 v35, v2
	v_mov_b32_e32 v36, v2
	v_mov_b32_e32 v37, v2
	v_mov_b32_e32 v38, v2
	v_mov_b32_e32 v39, v2
	v_mov_b32_e32 v40, v2
	v_mov_b32_e32 v41, v2
	v_mov_b32_e32 v42, v2
	v_mov_b32_e32 v43, v2
	v_mov_b32_e32 v44, v2
	v_mov_b32_e32 v45, v2
	v_mov_b32_e32 v46, v2
	v_mov_b32_e32 v47, v2
	v_mov_b32_e32 v48, v2
	v_mov_b32_e32 v49, v2
	v_mov_b32_e32 v50, v2
	v_mov_b32_e32 v51, v2
	v_mov_b32_e32 v52, v2
	v_mov_b32_e32 v53, v2
	v_mov_b32_e32 v54, v2
	v_mov_b32_e32 v55, v2
	v_mov_b32_e32 v56, v2
	v_mov_b32_e32 v57, v2
	v_mov_b32_e32 v58, v2
	v_mov_b32_e32 v59, v2
	v_mov_b32_e32 v60, v2
	v_mov_b32_e32 v61, v2
	v_mov_b32_e32 v62, v2
	v_mov_b32_e32 v63, v2
	v_mov_b32_e32 v64, v2
	v_mov_b32_e32 v65, v2
	v_mov_b32_e32 v66, v2
	v_mov_b32_e32 v67, v2
	v_mov_b32_e32 v68, v2
	v_mov_b32_e32 v69, v2
	v_mov_b32_e32 v70, v2
	v_mov_b32_e32 v71, v2
	v_mov_b32_e32 v72, v2
	v_mov_b32_e32 v73, v2
	v_mov_b32_e32 v74, v2
	v_mov_b32_e32 v75, v2
	v_mov_b32_e32 v76, v2
	v_mov_b32_e32 v77, v2
	v_mov_b32_e32 v78, v2
	v_mov_b32_e32 v79, v2
	v_mov_b32_e32 v80, v2
	v_mov_b32_e32 v81, v2
	v_mov_b32_e32 v82, v2
	v_mov_b32_e32 v83, v2
	v_mov_b32_e32 v84, v2
	v_mov_b32_e32 v85, v2
	v_mov_b32_e32 v86, v2
	v_mov_b32_e32 v87, v2
	v_mov_b32_e32 v88, v2
	v_mov_b32_e32 v89, v2
	v_mov_b32_e32 v90, v2
	v_mov_b32_e32 v91, v2
	v_mov_b32_e32 v92, v2
	v_mov_b32_e32 v93, v2
	v_mov_b32_e32 v94, v2
	v_mov_b32_e32 v95, v2
	v_mov_b32_e32 v96, v2
	v_mov_b32_e32 v97, v2
	s_waitcnt vmcnt(0)
	s_waitcnt lgkmcnt(0)
	s_barrier
	v_readfirstlane_b32 s4, v137
	v_lshrrev_b32_e32 v172, 6, v203
	s_nop 0
	v_readfirstlane_b32 s12, v172
	v_and_b32_e32 v172, 63, v203
	v_lshrrev_b32_e32 v173, 6, v203
	v_and_b32_e32 v174, 15, v172
	v_lshrrev_b32_e32 v175, 4, v172
	v_bfe_u32 v176, v172, 1, 3
	v_xor_b32_e32 v177, v175, v176
	v_lshlrev_b32_e32 v177, 4, v177
	v_or_b32_e32 v175, 4, v175
	v_xor_b32_e32 v175, v175, v176
	v_lshlrev_b32_e32 v175, 4, v175
	v_lshrrev_b32_e32 v176, 2, v173
	v_and_b32_e32 v173, 3, v173
	v_mul_u32_u24_e32 v176, 0x60, v176
	v_add_u32_e32 v176, v176, v174
	v_lshlrev_b32_e32 v176, 7, v176
	v_lshl_add_u32 v173, v173, 6, v174
	v_lshlrev_b32_e32 v173, 7, v173
	v_add_u32_e32 v173, 0x6020, v173
	v_add_u32_e32 v176, 32, v176
	v_add_u32_e32 v204, v176, v177
	v_add_u32_e32 v205, v176, v175
	v_add_u32_e32 v206, v173, v177
	v_add_u32_e32 v207, v173, v175
	s_cmp_ge_u32 s34, s84
	s_cbranch_scc1 .Lgk_last
